# attention fast path: row-sum adds as v_pk_add_f32 (17 instead of 33 VALU adds per tile)
# speedup vs baseline: 1.0192x; 1.0026x over previous
; #define LAS __attribute__((address_space(3)))
; #define MFMA32(a, b, c) __builtin_amdgcn_mfma_f32_32x32x16_bf16((a), (b), (c), 0, 0, 0)
; DI unsigned pk2(float lo, float hi) { f32x2_t v = {lo, hi}; bf16x2_t b = __builtin_convertvector(v, bf16x2_t); return __builtin_bit_cast(unsigned, b); }
; DI void attn_tile(bool MASK, const LAS unsigned char* Ks, const LAS unsigned char* Vs, const bf16x8 (&qr)[6], f32x16& negm, float& mrun, float& lrun, f32x16& o0, f32x16& o1,
;                                        int kv0, int qrow, int r32, int hi) {
;     ...
;     float ls = 0.f;
; #pragma unroll
;     for (int r = 0; r < 16; ++r) { p0[r] = __builtin_amdgcn_exp2f(p0[r]); p1[r] = __builtin_amdgcn_exp2f(p1[r]); ls += p0[r] + p1[r]; }
;     lrun += ls;
; #pragma unroll
;     for (int ks = 0; ks < 4; ++ks) {
;         u32x4 pp;
;         if (ks == 0) { pp.x = pk2(p0[0], p0[1]); pp.y = pk2(p0[2], p0[3]); pp.z = pk2(p0[4], p0[5]); pp.w = pk2(p0[6], p0[7]); }
;         else if (ks == 1) { pp.x = pk2(p0[8], p0[9]); pp.y = pk2(p0[10], p0[11]); pp.z = pk2(p0[12], p0[13]); pp.w = pk2(p0[14], p0[15]); }
;         else if (ks == 2) { pp.x = pk2(p1[0], p1[1]); pp.y = pk2(p1[2], p1[3]); pp.z = pk2(p1[4], p1[5]); pp.w = pk2(p1[6], p1[7]); }
;         else { pp.x = pk2(p1[8], p1[9]); pp.y = pk2(p1[10], p1[11]); pp.z = pk2(p1[12], p1[13]); pp.w = pk2(p1[14], p1[15]); }
;         const bf16x8 pa = __builtin_bit_cast(bf16x8, pp);
;         const LAS unsigned char* vp = Vs + r32 * 136 + (16 * ks + 4 * hi) * 2;
;         const u32x2 l0 = *(const LAS u32x2*)vp, h0 = *(const LAS u32x2*)(vp + 16);
;         const u32x2 l1 = *(const LAS u32x2*)(vp + 32 * 136), h1 = *(const LAS u32x2*)(vp + 32 * 136 + 16);
;         u32x4 v0 = {l0.x, l0.y, h0.x, h0.y}, v1 = {l1.x, l1.y, h1.x, h1.y};
;         o0 = MFMA32(__builtin_bit_cast(bf16x8, v0), pa, o0);
;         o1 = MFMA32(__builtin_bit_cast(bf16x8, v1), pa, o1);
;     }
.Lat_c0:
	v_cvt_pk_bf16_f32 v4, v214, v215
	v_cvt_pk_bf16_f32 v5, v216, v217
	v_cvt_pk_bf16_f32 v6, v218, v219
	v_cvt_pk_bf16_f32 v7, v220, v221
	v_exp_f32_e32 v66, v66
	v_exp_f32_e32 v67, v67
	s_waitcnt lgkmcnt(4)
	v_mfma_f32_32x32x16_bf16 v[32:47], v[226:229], v[4:7], v[32:47]
	v_mfma_f32_32x32x16_bf16 v[16:31], v[230:233], v[4:7], v[16:31]
	v_cvt_pk_bf16_f32 v8, v222, v223
	v_cvt_pk_bf16_f32 v9, v224, v225
	v_cvt_pk_bf16_f32 v10, v12, v13
	v_cvt_pk_bf16_f32 v11, v14, v15
	v_exp_f32_e32 v68, v68
	v_exp_f32_e32 v69, v69
	v_exp_f32_e32 v70, v70
	v_exp_f32_e32 v71, v71
	s_waitcnt lgkmcnt(2)
	v_mfma_f32_32x32x16_bf16 v[32:47], v[234:237], v[8:11], v[32:47]
	v_mfma_f32_32x32x16_bf16 v[16:31], v[238:241], v[8:11], v[16:31]
	v_add_u32_e32 v3, v205, v208
	v_add_u32_e32 v0, 0x4000, v3
	v_add_u32_e32 v3, 0x3000, v3
	ds_read2_b64 v[226:229], v3 offset0:140 offset1:142
	ds_read2_b64 v[230:233], v0 offset0:172 offset1:174
	v_exp_f32_e32 v72, v72
	v_exp_f32_e32 v73, v73
	v_pk_add_f32 v[82:83], v[214:215], v[66:67]
	v_pk_add_f32 v[84:85], v[216:217], v[68:69]
	v_cvt_pk_bf16_f32 v4, v66, v67
	v_cvt_pk_bf16_f32 v5, v68, v69
	v_cvt_pk_bf16_f32 v6, v70, v71
	v_cvt_pk_bf16_f32 v7, v72, v73
	v_exp_f32_e32 v74, v74
	v_exp_f32_e32 v75, v75
	v_exp_f32_e32 v76, v76
	v_exp_f32_e32 v77, v77
	s_waitcnt lgkmcnt(2)
	v_mfma_f32_32x32x16_bf16 v[32:47], v[242:245], v[4:7], v[32:47]
	v_mfma_f32_32x32x16_bf16 v[16:31], v[246:249], v[4:7], v[16:31]
	v_pk_add_f32 v[86:87], v[218:219], v[70:71]
	v_pk_add_f32 v[88:89], v[220:221], v[72:73]
	v_exp_f32_e32 v78, v78
	v_exp_f32_e32 v79, v79
	v_exp_f32_e32 v80, v80
	v_exp_f32_e32 v81, v81
	v_pk_add_f32 v[250:251], v[82:83], v[84:85]
	v_pk_add_f32 v[250:251], v[250:251], v[86:87]
	v_pk_add_f32 v[250:251], v[250:251], v[88:89]
	v_pk_add_f32 v[90:91], v[222:223], v[74:75]
	v_pk_add_f32 v[92:93], v[224:225], v[76:77]
	v_pk_add_f32 v[94:95], v[12:13], v[78:79]
	v_pk_add_f32 v[96:97], v[14:15], v[80:81]
	v_cvt_pk_bf16_f32 v8, v74, v75
	v_cvt_pk_bf16_f32 v9, v76, v77
	v_cvt_pk_bf16_f32 v10, v78, v79
	v_cvt_pk_bf16_f32 v11, v80, v81
	s_waitcnt lgkmcnt(0)
	s_nop 1
	v_mfma_f32_32x32x16_bf16 v[32:47], v[226:229], v[8:11], v[32:47]
	v_mfma_f32_32x32x16_bf16 v[16:31], v[230:233], v[8:11], v[16:31]
	v_pk_add_f32 v[250:251], v[250:251], v[90:91]
	v_pk_add_f32 v[250:251], v[250:251], v[92:93]
	v_pk_add_f32 v[250:251], v[250:251], v[94:95]
	v_pk_add_f32 v[250:251], v[250:251], v[96:97]
	v_add_f32_e32 v251, v250, v251
	v_add_f32_e32 v48, v48, v251
	s_branch .LBB0_855

; #define LAS __attribute__((address_space(3)))
; #define MFMA32(a, b, c) __builtin_amdgcn_mfma_f32_32x32x16_bf16((a), (b), (c), 0, 0, 0)
; DI unsigned pk2(float lo, float hi) { f32x2_t v = {lo, hi}; bf16x2_t b = __builtin_convertvector(v, bf16x2_t); return __builtin_bit_cast(unsigned, b); }
; DI void attn_tile(bool MASK, const LAS unsigned char* Ks, const LAS unsigned char* Vs, const bf16x8 (&qr)[6], f32x16& negm, float& mrun, float& lrun, f32x16& o0, f32x16& o1,
;                                        int kv0, int qrow, int r32, int hi) {
;     ...
;     float ls = 0.f;
; #pragma unroll
;     for (int r = 0; r < 16; ++r) { p0[r] = __builtin_amdgcn_exp2f(p0[r]); p1[r] = __builtin_amdgcn_exp2f(p1[r]); ls += p0[r] + p1[r]; }
;     lrun += ls;
; #pragma unroll
;     for (int ks = 0; ks < 4; ++ks) {
;         u32x4 pp;
;         if (ks == 0) { pp.x = pk2(p0[0], p0[1]); pp.y = pk2(p0[2], p0[3]); pp.z = pk2(p0[4], p0[5]); pp.w = pk2(p0[6], p0[7]); }
;         else if (ks == 1) { pp.x = pk2(p0[8], p0[9]); pp.y = pk2(p0[10], p0[11]); pp.z = pk2(p0[12], p0[13]); pp.w = pk2(p0[14], p0[15]); }
;         else if (ks == 2) { pp.x = pk2(p1[0], p1[1]); pp.y = pk2(p1[2], p1[3]); pp.z = pk2(p1[4], p1[5]); pp.w = pk2(p1[6], p1[7]); }
;         else { pp.x = pk2(p1[8], p1[9]); pp.y = pk2(p1[10], p1[11]); pp.z = pk2(p1[12], p1[13]); pp.w = pk2(p1[14], p1[15]); }
;         const bf16x8 pa = __builtin_bit_cast(bf16x8, pp);
;         const LAS unsigned char* vp = Vs + r32 * 136 + (16 * ks + 4 * hi) * 2;
;         const u32x2 l0 = *(const LAS u32x2*)vp, h0 = *(const LAS u32x2*)(vp + 16);
;         const u32x2 l1 = *(const LAS u32x2*)(vp + 32 * 136), h1 = *(const LAS u32x2*)(vp + 32 * 136 + 16);
;         u32x4 v0 = {l0.x, l0.y, h0.x, h0.y}, v1 = {l1.x, l1.y, h1.x, h1.y};
;         o0 = MFMA32(__builtin_bit_cast(bf16x8, v0), pa, o0);
;         o1 = MFMA32(__builtin_bit_cast(bf16x8, v1), pa, o1);
;     }
.Lat_c1:
	v_cvt_pk_bf16_f32 v4, v214, v215
	v_cvt_pk_bf16_f32 v5, v216, v217
	v_cvt_pk_bf16_f32 v6, v218, v219
	v_cvt_pk_bf16_f32 v7, v220, v221
	v_exp_f32_e32 v66, v66
	v_exp_f32_e32 v67, v67
	s_waitcnt lgkmcnt(4)
	v_mfma_f32_32x32x16_bf16 v[32:47], v[226:229], v[4:7], v[32:47]
	v_mfma_f32_32x32x16_bf16 v[16:31], v[230:233], v[4:7], v[16:31]
	v_cvt_pk_bf16_f32 v8, v222, v223
	v_cvt_pk_bf16_f32 v9, v224, v225
	v_cvt_pk_bf16_f32 v10, v12, v13
	v_cvt_pk_bf16_f32 v11, v14, v15
	v_exp_f32_e32 v68, v68
	v_exp_f32_e32 v69, v69
	v_exp_f32_e32 v70, v70
	v_exp_f32_e32 v71, v71
	s_waitcnt lgkmcnt(2)
	v_mfma_f32_32x32x16_bf16 v[32:47], v[234:237], v[8:11], v[32:47]
	v_mfma_f32_32x32x16_bf16 v[16:31], v[238:241], v[8:11], v[16:31]
	v_add_u32_e32 v3, v205, v208
	v_add_u32_e32 v0, 0x9800, v3
	v_add_u32_e32 v3, 0x8800, v3
	ds_read2_b64 v[226:229], v3 offset0:76 offset1:78
	ds_read2_b64 v[230:233], v0 offset0:108 offset1:110
	v_exp_f32_e32 v72, v72
	v_exp_f32_e32 v73, v73
	v_pk_add_f32 v[82:83], v[214:215], v[66:67]
	v_pk_add_f32 v[84:85], v[216:217], v[68:69]
	v_cvt_pk_bf16_f32 v4, v66, v67
	v_cvt_pk_bf16_f32 v5, v68, v69
	v_cvt_pk_bf16_f32 v6, v70, v71
	v_cvt_pk_bf16_f32 v7, v72, v73
	v_exp_f32_e32 v74, v74
	v_exp_f32_e32 v75, v75
	v_exp_f32_e32 v76, v76
	v_exp_f32_e32 v77, v77
	s_waitcnt lgkmcnt(2)
	v_mfma_f32_32x32x16_bf16 v[32:47], v[242:245], v[4:7], v[32:47]
	v_mfma_f32_32x32x16_bf16 v[16:31], v[246:249], v[4:7], v[16:31]
	v_pk_add_f32 v[86:87], v[218:219], v[70:71]
	v_pk_add_f32 v[88:89], v[220:221], v[72:73]
	v_exp_f32_e32 v78, v78
	v_exp_f32_e32 v79, v79
	v_exp_f32_e32 v80, v80
	v_exp_f32_e32 v81, v81
	v_pk_add_f32 v[250:251], v[82:83], v[84:85]
	v_pk_add_f32 v[250:251], v[250:251], v[86:87]
	v_pk_add_f32 v[250:251], v[250:251], v[88:89]
	v_pk_add_f32 v[90:91], v[222:223], v[74:75]
	v_pk_add_f32 v[92:93], v[224:225], v[76:77]
	v_pk_add_f32 v[94:95], v[12:13], v[78:79]
	v_pk_add_f32 v[96:97], v[14:15], v[80:81]
	v_cvt_pk_bf16_f32 v8, v74, v75
	v_cvt_pk_bf16_f32 v9, v76, v77
	v_cvt_pk_bf16_f32 v10, v78, v79
	v_cvt_pk_bf16_f32 v11, v80, v81
	s_waitcnt lgkmcnt(0)
	s_nop 1
	v_mfma_f32_32x32x16_bf16 v[32:47], v[226:229], v[8:11], v[32:47]
	v_mfma_f32_32x32x16_bf16 v[16:31], v[230:233], v[8:11], v[16:31]
	v_pk_add_f32 v[250:251], v[250:251], v[90:91]
	v_pk_add_f32 v[250:251], v[250:251], v[92:93]
	v_pk_add_f32 v[250:251], v[250:251], v[94:95]
	v_pk_add_f32 v[250:251], v[250:251], v[96:97]
	v_add_f32_e32 v251, v250, v251
	v_add_f32_e32 v48, v48, v251
	s_branch .LBB0_862

; #define LAS __attribute__((address_space(3)))
; #define MFMA32(a, b, c) __builtin_amdgcn_mfma_f32_32x32x16_bf16((a), (b), (c), 0, 0, 0)
; DI unsigned pk2(float lo, float hi) { f32x2_t v = {lo, hi}; bf16x2_t b = __builtin_convertvector(v, bf16x2_t); return __builtin_bit_cast(unsigned, b); }
; DI void attn_tile(bool MASK, const LAS unsigned char* Ks, const LAS unsigned char* Vs, const bf16x8 (&qr)[6], f32x16& negm, float& mrun, float& lrun, f32x16& o0, f32x16& o1,
;                                        int kv0, int qrow, int r32, int hi) {
;     ...
;     float ls = 0.f;
; #pragma unroll
;     for (int r = 0; r < 16; ++r) { p0[r] = __builtin_amdgcn_exp2f(p0[r]); p1[r] = __builtin_amdgcn_exp2f(p1[r]); ls += p0[r] + p1[r]; }
;     lrun += ls;
; #pragma unroll
;     for (int ks = 0; ks < 4; ++ks) {
;         u32x4 pp;
;         if (ks == 0) { pp.x = pk2(p0[0], p0[1]); pp.y = pk2(p0[2], p0[3]); pp.z = pk2(p0[4], p0[5]); pp.w = pk2(p0[6], p0[7]); }
;         else if (ks == 1) { pp.x = pk2(p0[8], p0[9]); pp.y = pk2(p0[10], p0[11]); pp.z = pk2(p0[12], p0[13]); pp.w = pk2(p0[14], p0[15]); }
;         else if (ks == 2) { pp.x = pk2(p1[0], p1[1]); pp.y = pk2(p1[2], p1[3]); pp.z = pk2(p1[4], p1[5]); pp.w = pk2(p1[6], p1[7]); }
;         else { pp.x = pk2(p1[8], p1[9]); pp.y = pk2(p1[10], p1[11]); pp.z = pk2(p1[12], p1[13]); pp.w = pk2(p1[14], p1[15]); }
;         const bf16x8 pa = __builtin_bit_cast(bf16x8, pp);
;         const LAS unsigned char* vp = Vs + r32 * 136 + (16 * ks + 4 * hi) * 2;
;         const u32x2 l0 = *(const LAS u32x2*)vp, h0 = *(const LAS u32x2*)(vp + 16);
;         const u32x2 l1 = *(const LAS u32x2*)(vp + 32 * 136), h1 = *(const LAS u32x2*)(vp + 32 * 136 + 16);
;         u32x4 v0 = {l0.x, l0.y, h0.x, h0.y}, v1 = {l1.x, l1.y, h1.x, h1.y};
;         o0 = MFMA32(__builtin_bit_cast(bf16x8, v0), pa, o0);
;         o1 = MFMA32(__builtin_bit_cast(bf16x8, v1), pa, o1);
;     }
.Lat_c2:
	v_cvt_pk_bf16_f32 v4, v214, v215
	v_cvt_pk_bf16_f32 v5, v216, v217
	v_cvt_pk_bf16_f32 v6, v218, v219
	v_cvt_pk_bf16_f32 v7, v220, v221
	v_exp_f32_e32 v66, v66
	v_exp_f32_e32 v67, v67
	s_waitcnt lgkmcnt(4)
	v_mfma_f32_32x32x16_bf16 v[32:47], v[226:229], v[4:7], v[32:47]
	v_mfma_f32_32x32x16_bf16 v[16:31], v[230:233], v[4:7], v[16:31]
	v_cvt_pk_bf16_f32 v8, v222, v223
	v_cvt_pk_bf16_f32 v9, v224, v225
	v_cvt_pk_bf16_f32 v10, v12, v13
	v_cvt_pk_bf16_f32 v11, v14, v15
	v_exp_f32_e32 v68, v68
	v_exp_f32_e32 v69, v69
	v_exp_f32_e32 v70, v70
	v_exp_f32_e32 v71, v71
	s_waitcnt lgkmcnt(2)
	v_mfma_f32_32x32x16_bf16 v[32:47], v[234:237], v[8:11], v[32:47]
	v_mfma_f32_32x32x16_bf16 v[16:31], v[238:241], v[8:11], v[16:31]
	v_add_u32_e32 v3, v205, v208
	v_add_u32_e32 v0, 0xf000, v3
	v_add_u32_e32 v3, 0xe000, v3
	ds_read2_b64 v[226:229], v3 offset0:12 offset1:14
	ds_read2_b64 v[230:233], v0 offset0:44 offset1:46
	v_exp_f32_e32 v72, v72
	v_exp_f32_e32 v73, v73
	v_pk_add_f32 v[82:83], v[214:215], v[66:67]
	v_pk_add_f32 v[84:85], v[216:217], v[68:69]
	v_cvt_pk_bf16_f32 v4, v66, v67
	v_cvt_pk_bf16_f32 v5, v68, v69
	v_cvt_pk_bf16_f32 v6, v70, v71
	v_cvt_pk_bf16_f32 v7, v72, v73
	v_exp_f32_e32 v74, v74
	v_exp_f32_e32 v75, v75
	v_exp_f32_e32 v76, v76
	v_exp_f32_e32 v77, v77
	s_waitcnt lgkmcnt(2)
	v_mfma_f32_32x32x16_bf16 v[32:47], v[242:245], v[4:7], v[32:47]
	v_mfma_f32_32x32x16_bf16 v[16:31], v[246:249], v[4:7], v[16:31]
	v_pk_add_f32 v[86:87], v[218:219], v[70:71]
	v_pk_add_f32 v[88:89], v[220:221], v[72:73]
	v_exp_f32_e32 v78, v78
	v_exp_f32_e32 v79, v79
	v_exp_f32_e32 v80, v80
	v_exp_f32_e32 v81, v81
	v_pk_add_f32 v[250:251], v[82:83], v[84:85]
	v_pk_add_f32 v[250:251], v[250:251], v[86:87]
	v_pk_add_f32 v[250:251], v[250:251], v[88:89]
	v_pk_add_f32 v[90:91], v[222:223], v[74:75]
	v_pk_add_f32 v[92:93], v[224:225], v[76:77]
	v_pk_add_f32 v[94:95], v[12:13], v[78:79]
	v_pk_add_f32 v[96:97], v[14:15], v[80:81]
	v_cvt_pk_bf16_f32 v8, v74, v75
	v_cvt_pk_bf16_f32 v9, v76, v77
	v_cvt_pk_bf16_f32 v10, v78, v79
	v_cvt_pk_bf16_f32 v11, v80, v81
	s_waitcnt lgkmcnt(0)
	s_nop 1
	v_mfma_f32_32x32x16_bf16 v[32:47], v[226:229], v[8:11], v[32:47]
	v_mfma_f32_32x32x16_bf16 v[16:31], v[230:233], v[8:11], v[16:31]
	v_pk_add_f32 v[250:251], v[250:251], v[90:91]
	v_pk_add_f32 v[250:251], v[250:251], v[92:93]
	v_pk_add_f32 v[250:251], v[250:251], v[94:95]
	v_pk_add_f32 v[250:251], v[250:251], v[96:97]
	v_add_f32_e32 v251, v250, v251
	v_add_f32_e32 v48, v48, v251
	s_branch .LBB0_848
